# grid barrier: the releasing leader no longer waits for the acks of its fire-and-forget release atomics (its invalidate is already complete)
# speedup vs baseline: 1.0006x; 1.0006x over previous
.LBB0_604:
	s_or_b64 exec, exec, s[4:5]
.LBB0_605:
	s_or_b64 exec, exec, s[0:1]
	s_mov_b64 s[0:1], 0
	s_waitcnt lgkmcnt(0)
	s_barrier
